# v45: v44 + in-proj K-loop load-section scalar set-up (m0, DMA base adds) issued inside the preceding MFMA sections
# speedup vs baseline: 1.0282x; 1.0054x over previous
; #define G_STAGE(bufoff, gbase, voff) do { _Pragma("unroll") for (int _i = 0; _i < 2; ++_i) \
;     __builtin_amdgcn_global_load_lds((const unsigned*)((const char*)(gbase) + (voff)[_i]), (LAS unsigned*)(lds + (bufoff) + ldsw + _i * 8192), 16, 0, 0); } while (0)
; #define G_LDA(dst, b, h) do { _Pragma("unroll") for (int m = 0; m < 4; ++m) _Pragma("unroll") for (int k = 0; k < 2; ++k) dst[m][k] = *(const LAS bf16x8*)(lds + G_SA(b, h) + aoff + m * 2048 + k * 1024); } while (0)
; #define G_LDB(dst, b, h) do { _Pragma("unroll") for (int n = 0; n < 2; ++n) _Pragma("unroll") for (int k = 0; k < 2; ++k) dst[n][k] = *(const LAS bf16x8*)(lds + G_SB(b, h) + boff + n * 2048 + k * 1024); } while (0)
; #define G_MMA(ai, bj, At, Bt) do { __builtin_amdgcn_s_setprio(1); _Pragma("unroll") for (int m = 0; m < 4; ++m) _Pragma("unroll") for (int n = 0; n < 2; ++n) _Pragma("unroll") for (int k = 0; k < 2; ++k) \
;     acc[ai][bj][m][n] = __builtin_amdgcn_mfma_f32_16x16x32_bf16(Bt[n][k], At[m][k], acc[ai][bj][m][n], 0, 0, 0); __builtin_amdgcn_s_setprio(0); } while (0)
; template <int GP> DI void gemm_phase(const Params& p, int l, int which, char* smem, int wv) {
;     ...
;     const char* nA = has_next ? (const char*)Aglob + (size_t)nmt * tstep + (size_t)nk0 * 2 : cA;
;     const char* nB = has_next ? (const char*)Wt + (size_t)nnt * tstep + (size_t)nk0 * 2 : cB;
;     const bool n32 = has_next ? ((!which) && (nnt < 4)) : c32;
;     for (int t = 0; t < cnk; t += 2) {
;       const bool last = (t == cnk - 2);
;       const char* a1 = cA + (size_t)(t + 1) * kstep;
;       const char* a2 = last ? nA : cA + (size_t)(t + 2) * kstep; const char* b2 = last ? nB : cB + (size_t)(t + 2) * kstep;
;       const char* a3 = a2 + kstep; const char* b3 = b2 + kstep;
;       if (last) {
; #pragma unroll
;         for (int i = 0; i < 2; ++i) { vb0[i] = voffB(i, 0, n32); vb1[i] = voffB(i, 1, n32); }
;       }
;       G_LDB(B0, 0, 0); G_SCHED; G_LDA(At, 0, 0); G_STAGE(G_SA(1, 1), a1 + hstep, voffA);
;       G_WAIT_L(8); G_BAR; G_WAIT_L(0); G_MMA(0, 0, At, B0); G_BAR; G_SCHED;
;       G_LDB(B1, 0, 1); G_STAGE(G_SB(0, 0), b2, vb0);
;       G_BAR; G_WAIT_L(0); G_MMA(0, 1, At, B1); G_BAR;
;       G_LDA(At, 0, 1); G_STAGE(G_SA(0, 0), a2, voffA);
;       G_BAR; G_WAIT_L(0); G_MMA(1, 0, At, B0); G_BAR; G_SCHED;
;       G_STAGE(G_SB(0, 1), b2, vb1);
;       G_WAIT_V(6); G_BAR; G_MMA(1, 1, At, B1); G_BAR;
.LBB0_209:
	s_add_i32 m0, s23, 0xc000
	s_add_u32 s8, s28, s2
	v_add_u32_e32 v228, 0x10000, v212
	s_addc_u32 s9, s29, s3
	s_add_u32 s100, s8, 0x80080
	s_addc_u32 s101, s9, 0
	s_add_u32 s52, s8, 0x100
	s_addc_u32 s53, s9, 0
	s_and_b64 s[8:9], s[6:7], exec
	s_cselect_b32 s9, s10, s53
	s_cselect_b32 s8, s11, s52
	s_add_u32 s52, s74, s2
	s_addc_u32 s53, s75, s3
	s_and_b64 s[6:7], s[6:7], exec
	s_cselect_b32 s7, s37, s53
	s_cselect_b32 s6, s39, s52
.Lkf_top:
	ds_read_b128 v[148:151], v228
	ds_read_b128 v[152:155], v228 offset:1024
	ds_read_b128 v[156:159], v228 offset:2048
	ds_read_b128 v[160:163], v228 offset:3072
	ds_read_b128 v[164:167], v211
	ds_read_b128 v[168:171], v211 offset:1024
	ds_read_b128 v[172:175], v211 offset:2048
	ds_read_b128 v[176:179], v211 offset:3072
	ds_read_b128 v[180:183], v211 offset:4096
	ds_read_b128 v[184:187], v211 offset:5120
	ds_read_b128 v[188:191], v211 offset:6144
	ds_read_b128 v[192:195], v211 offset:7168
	global_load_lds_dwordx4 v138, s[100:101]
	s_add_i32 m0, s23, 0xe000
	s_nop 0
	global_load_lds_dwordx4 v140, s[100:101]
	s_waitcnt lgkmcnt(8)
	s_barrier
	s_waitcnt lgkmcnt(0)
	s_waitcnt lgkmcnt(0)
	v_mfma_f32_16x16x32_bf16 v[62:65], v[148:151], v[164:167], v[62:65]
	v_mfma_f32_16x16x32_bf16 v[58:61], v[156:159], v[164:167], v[58:61]
	s_mov_b32 m0, s25
	v_mfma_f32_16x16x32_bf16 v[54:57], v[148:151], v[172:175], v[54:57]
	v_mfma_f32_16x16x32_bf16 v[50:53], v[156:159], v[172:175], v[50:53]
	v_mfma_f32_16x16x32_bf16 v[46:49], v[148:151], v[180:183], v[46:49]
	v_mfma_f32_16x16x32_bf16 v[42:45], v[156:159], v[180:183], v[42:45]
	v_mfma_f32_16x16x32_bf16 v[38:41], v[148:151], v[188:191], v[38:41]
	v_mfma_f32_16x16x32_bf16 v[34:37], v[156:159], v[188:191], v[34:37]
	v_mfma_f32_16x16x32_bf16 v[62:65], v[152:155], v[168:171], v[62:65]
	v_mfma_f32_16x16x32_bf16 v[58:61], v[160:163], v[168:171], v[58:61]
	v_mfma_f32_16x16x32_bf16 v[54:57], v[152:155], v[176:179], v[54:57]
	v_mfma_f32_16x16x32_bf16 v[50:53], v[160:163], v[176:179], v[50:53]
	v_mfma_f32_16x16x32_bf16 v[46:49], v[152:155], v[184:187], v[46:49]
	v_mfma_f32_16x16x32_bf16 v[42:45], v[160:163], v[184:187], v[42:45]
	v_mfma_f32_16x16x32_bf16 v[38:41], v[152:155], v[192:195], v[38:41]
	v_mfma_f32_16x16x32_bf16 v[34:37], v[160:163], v[192:195], v[34:37]
	s_barrier
	ds_read_b128 v[196:199], v228 offset:16384
	ds_read_b128 v[200:203], v228 offset:17408
	ds_read_b128 v[204:207], v228 offset:18432
	ds_read_b128 v[238:241], v228 offset:19456
	global_load_lds_dwordx4 v0, s[6:7]
	s_mov_b32 m0, s58
	s_nop 0
	global_load_lds_dwordx4 v136, s[6:7]
	s_barrier
	s_waitcnt lgkmcnt(0)
	s_waitcnt lgkmcnt(0)
	v_mfma_f32_16x16x32_bf16 v[30:33], v[196:199], v[164:167], v[30:33]
	v_mfma_f32_16x16x32_bf16 v[26:29], v[204:207], v[164:167], v[26:29]
	s_mov_b32 m0, s23
	v_mfma_f32_16x16x32_bf16 v[22:25], v[196:199], v[172:175], v[22:25]
	v_mfma_f32_16x16x32_bf16 v[18:21], v[204:207], v[172:175], v[18:21]
	v_mfma_f32_16x16x32_bf16 v[14:17], v[196:199], v[180:183], v[14:17]
	v_mfma_f32_16x16x32_bf16 v[10:13], v[204:207], v[180:183], v[10:13]
	v_mfma_f32_16x16x32_bf16 v[6:9], v[196:199], v[188:191], v[6:9]
	v_mfma_f32_16x16x32_bf16 v[2:5], v[204:207], v[188:191], v[2:5]
	v_mfma_f32_16x16x32_bf16 v[30:33], v[200:203], v[168:171], v[30:33]
	v_mfma_f32_16x16x32_bf16 v[26:29], v[238:241], v[168:171], v[26:29]
	v_mfma_f32_16x16x32_bf16 v[22:25], v[200:203], v[176:179], v[22:25]
	v_mfma_f32_16x16x32_bf16 v[18:21], v[238:241], v[176:179], v[18:21]
	v_mfma_f32_16x16x32_bf16 v[14:17], v[200:203], v[184:187], v[14:17]
	v_mfma_f32_16x16x32_bf16 v[10:13], v[238:241], v[184:187], v[10:13]
	v_mfma_f32_16x16x32_bf16 v[6:9], v[200:203], v[192:195], v[6:9]
	v_mfma_f32_16x16x32_bf16 v[2:5], v[238:241], v[192:195], v[2:5]
	s_barrier
	ds_read_b128 v[164:167], v211 offset:16384
	ds_read_b128 v[168:171], v211 offset:17408
	ds_read_b128 v[172:175], v211 offset:18432
	ds_read_b128 v[176:179], v211 offset:19456
	ds_read_b128 v[180:183], v211 offset:20480
	ds_read_b128 v[184:187], v211 offset:21504
	ds_read_b128 v[188:191], v211 offset:22528
	ds_read_b128 v[192:195], v211 offset:23552
	global_load_lds_dwordx4 v132, s[8:9]
	s_mov_b32 m0, s59
	s_nop 0
	global_load_lds_dwordx4 v134, s[8:9]
	s_barrier
	s_waitcnt lgkmcnt(0)
	s_waitcnt lgkmcnt(0)
	v_mfma_f32_16x16x32_bf16 v[66:69], v[148:151], v[164:167], v[66:69]
	v_mfma_f32_16x16x32_bf16 v[70:73], v[156:159], v[164:167], v[70:73]
	s_mov_b32 m0, s60
	v_mfma_f32_16x16x32_bf16 v[74:77], v[148:151], v[172:175], v[74:77]
	v_mfma_f32_16x16x32_bf16 v[78:81], v[156:159], v[172:175], v[78:81]
	v_mfma_f32_16x16x32_bf16 v[82:85], v[148:151], v[180:183], v[82:85]
	v_mfma_f32_16x16x32_bf16 v[86:89], v[156:159], v[180:183], v[86:89]
	v_mfma_f32_16x16x32_bf16 v[90:93], v[148:151], v[188:191], v[90:93]
	v_mfma_f32_16x16x32_bf16 v[94:97], v[156:159], v[188:191], v[94:97]
	v_mfma_f32_16x16x32_bf16 v[66:69], v[152:155], v[168:171], v[66:69]
	v_mfma_f32_16x16x32_bf16 v[70:73], v[160:163], v[168:171], v[70:73]
	v_mfma_f32_16x16x32_bf16 v[74:77], v[152:155], v[176:179], v[74:77]
	v_mfma_f32_16x16x32_bf16 v[78:81], v[160:163], v[176:179], v[78:81]
	v_mfma_f32_16x16x32_bf16 v[82:85], v[152:155], v[184:187], v[82:85]
	v_mfma_f32_16x16x32_bf16 v[86:89], v[160:163], v[184:187], v[86:89]
	v_mfma_f32_16x16x32_bf16 v[90:93], v[152:155], v[192:195], v[90:93]
	v_mfma_f32_16x16x32_bf16 v[94:97], v[160:163], v[192:195], v[94:97]
	s_barrier
	global_load_lds_dwordx4 v130, s[6:7]
	s_mov_b32 m0, s61
	s_nop 0
	global_load_lds_dwordx4 v142, s[6:7]
	s_waitcnt vmcnt(6)
	s_barrier
; #define G_STAGE(bufoff, gbase, voff) do { _Pragma("unroll") for (int _i = 0; _i < 2; ++_i) \
;     __builtin_amdgcn_global_load_lds((const unsigned*)((const char*)(gbase) + (voff)[_i]), (LAS unsigned*)(lds + (bufoff) + ldsw + _i * 8192), 16, 0, 0); } while (0)
; #define G_LDA(dst, b, h) do { _Pragma("unroll") for (int m = 0; m < 4; ++m) _Pragma("unroll") for (int k = 0; k < 2; ++k) dst[m][k] = *(const LAS bf16x8*)(lds + G_SA(b, h) + aoff + m * 2048 + k * 1024); } while (0)
; #define G_LDB(dst, b, h) do { _Pragma("unroll") for (int n = 0; n < 2; ++n) _Pragma("unroll") for (int k = 0; k < 2; ++k) dst[n][k] = *(const LAS bf16x8*)(lds + G_SB(b, h) + boff + n * 2048 + k * 1024); } while (0)
; #define G_MMA(ai, bj, At, Bt) do { __builtin_amdgcn_s_setprio(1); _Pragma("unroll") for (int m = 0; m < 4; ++m) _Pragma("unroll") for (int n = 0; n < 2; ++n) _Pragma("unroll") for (int k = 0; k < 2; ++k) \
;     acc[ai][bj][m][n] = __builtin_amdgcn_mfma_f32_16x16x32_bf16(Bt[n][k], At[m][k], acc[ai][bj][m][n], 0, 0, 0); __builtin_amdgcn_s_setprio(0); } while (0)
; #define G_WAIT_V(n) asm volatile("s_waitcnt vmcnt(" #n ")" ::: "memory")
; #define G_WAIT_L(n) asm volatile("s_waitcnt lgkmcnt(" #n ")" ::: "memory")
; #define G_BAR __builtin_amdgcn_s_barrier()
; #define G_SCHED __builtin_amdgcn_sched_barrier(0)
; template <int GP> DI void gemm_phase(const Params& p, int l, int which, char* smem, int wv) {
;     ...
;       G_WAIT_V(6); G_BAR; G_MMA(1, 1, At, B1); G_BAR;
;       G_LDB(B0, 1, 0); G_SCHED; G_LDA(At, 1, 0); G_STAGE(G_SA(0, 1), a2 + hstep, voffA);
;       G_WAIT_L(8); G_BAR; G_WAIT_L(0); G_MMA(0, 0, At, B0); G_BAR; G_SCHED;
;       G_LDB(B1, 1, 1); G_STAGE(G_SB(1, 0), b3, vb0);
	v_mfma_f32_16x16x32_bf16 v[98:101], v[196:199], v[164:167], v[98:101]
	v_mfma_f32_16x16x32_bf16 v[102:105], v[204:207], v[164:167], v[102:105]
	s_add_u32 s100, s8, 0x80000
	s_addc_u32 s101, s9, 0
	s_mov_b32 m0, s62
	v_mfma_f32_16x16x32_bf16 v[106:109], v[196:199], v[172:175], v[106:109]
	v_mfma_f32_16x16x32_bf16 v[110:113], v[204:207], v[172:175], v[110:113]
	v_mfma_f32_16x16x32_bf16 v[114:117], v[196:199], v[180:183], v[114:117]
	v_mfma_f32_16x16x32_bf16 v[118:121], v[204:207], v[180:183], v[118:121]
	v_mfma_f32_16x16x32_bf16 v[122:125], v[196:199], v[188:191], v[122:125]
	v_mfma_f32_16x16x32_bf16 v[126:129], v[204:207], v[188:191], v[126:129]
	v_mfma_f32_16x16x32_bf16 v[98:101], v[200:203], v[168:171], v[98:101]
	v_mfma_f32_16x16x32_bf16 v[102:105], v[238:241], v[168:171], v[102:105]
	v_mfma_f32_16x16x32_bf16 v[106:109], v[200:203], v[176:179], v[106:109]
	v_mfma_f32_16x16x32_bf16 v[110:113], v[238:241], v[176:179], v[110:113]
	v_mfma_f32_16x16x32_bf16 v[114:117], v[200:203], v[184:187], v[114:117]
	v_mfma_f32_16x16x32_bf16 v[118:121], v[238:241], v[184:187], v[118:121]
	v_mfma_f32_16x16x32_bf16 v[122:125], v[200:203], v[192:195], v[122:125]
	v_mfma_f32_16x16x32_bf16 v[126:129], v[238:241], v[192:195], v[126:129]
	s_barrier
	ds_read_b128 v[148:151], v228 offset:32768
	ds_read_b128 v[152:155], v228 offset:33792
	ds_read_b128 v[156:159], v228 offset:34816
	ds_read_b128 v[160:163], v228 offset:35840
	ds_read_b128 v[164:167], v211 offset:32768
	ds_read_b128 v[168:171], v211 offset:33792
	ds_read_b128 v[172:175], v211 offset:34816
	ds_read_b128 v[176:179], v211 offset:35840
	ds_read_b128 v[180:183], v211 offset:36864
	ds_read_b128 v[184:187], v211 offset:37888
	ds_read_b128 v[188:191], v211 offset:38912
	ds_read_b128 v[192:195], v211 offset:39936
	global_load_lds_dwordx4 v132, s[100:101]
	s_mov_b32 m0, s63
	s_nop 0
	global_load_lds_dwordx4 v134, s[100:101]
	s_waitcnt lgkmcnt(8)
	s_barrier
	s_waitcnt lgkmcnt(0)
	s_waitcnt lgkmcnt(0)
	v_mfma_f32_16x16x32_bf16 v[62:65], v[148:151], v[164:167], v[62:65]
	v_mfma_f32_16x16x32_bf16 v[58:61], v[156:159], v[164:167], v[58:61]
	s_mov_b32 m0, s21
	s_add_u32 s100, s6, s16
	s_addc_u32 s101, s7, s17
	v_mfma_f32_16x16x32_bf16 v[54:57], v[148:151], v[172:175], v[54:57]
	v_mfma_f32_16x16x32_bf16 v[50:53], v[156:159], v[172:175], v[50:53]
	v_mfma_f32_16x16x32_bf16 v[46:49], v[148:151], v[180:183], v[46:49]
	v_mfma_f32_16x16x32_bf16 v[42:45], v[156:159], v[180:183], v[42:45]
	v_mfma_f32_16x16x32_bf16 v[38:41], v[148:151], v[188:191], v[38:41]
	v_mfma_f32_16x16x32_bf16 v[34:37], v[156:159], v[188:191], v[34:37]
	v_mfma_f32_16x16x32_bf16 v[62:65], v[152:155], v[168:171], v[62:65]
	v_mfma_f32_16x16x32_bf16 v[58:61], v[160:163], v[168:171], v[58:61]
	v_mfma_f32_16x16x32_bf16 v[54:57], v[152:155], v[176:179], v[54:57]
	v_mfma_f32_16x16x32_bf16 v[50:53], v[160:163], v[176:179], v[50:53]
	v_mfma_f32_16x16x32_bf16 v[46:49], v[152:155], v[184:187], v[46:49]
	v_mfma_f32_16x16x32_bf16 v[42:45], v[160:163], v[184:187], v[42:45]
	v_mfma_f32_16x16x32_bf16 v[38:41], v[152:155], v[192:195], v[38:41]
	v_mfma_f32_16x16x32_bf16 v[34:37], v[160:163], v[192:195], v[34:37]
	s_barrier
	ds_read_b128 v[196:199], v228 offset:49152
	ds_read_b128 v[200:203], v228 offset:50176
	ds_read_b128 v[204:207], v228 offset:51200
	ds_read_b128 v[238:241], v228 offset:52224
	global_load_lds_dwordx4 v0, s[100:101]
	s_mov_b32 m0, s64
	s_nop 0
	global_load_lds_dwordx4 v136, s[100:101]
	s_barrier
; #define G_STAGE(bufoff, gbase, voff) do { _Pragma("unroll") for (int _i = 0; _i < 2; ++_i) \
;     __builtin_amdgcn_global_load_lds((const unsigned*)((const char*)(gbase) + (voff)[_i]), (LAS unsigned*)(lds + (bufoff) + ldsw + _i * 8192), 16, 0, 0); } while (0)
; #define G_LDA(dst, b, h) do { _Pragma("unroll") for (int m = 0; m < 4; ++m) _Pragma("unroll") for (int k = 0; k < 2; ++k) dst[m][k] = *(const LAS bf16x8*)(lds + G_SA(b, h) + aoff + m * 2048 + k * 1024); } while (0)
; #define G_LDB(dst, b, h) do { _Pragma("unroll") for (int n = 0; n < 2; ++n) _Pragma("unroll") for (int k = 0; k < 2; ++k) dst[n][k] = *(const LAS bf16x8*)(lds + G_SB(b, h) + boff + n * 2048 + k * 1024); } while (0)
; #define G_MMA(ai, bj, At, Bt) do { __builtin_amdgcn_s_setprio(1); _Pragma("unroll") for (int m = 0; m < 4; ++m) _Pragma("unroll") for (int n = 0; n < 2; ++n) _Pragma("unroll") for (int k = 0; k < 2; ++k) \
;     acc[ai][bj][m][n] = __builtin_amdgcn_mfma_f32_16x16x32_bf16(Bt[n][k], At[m][k], acc[ai][bj][m][n], 0, 0, 0); __builtin_amdgcn_s_setprio(0); } while (0)
; #define G_WAIT_V(n) asm volatile("s_waitcnt vmcnt(" #n ")" ::: "memory")
; #define G_WAIT_L(n) asm volatile("s_waitcnt lgkmcnt(" #n ")" ::: "memory")
; #define G_BAR __builtin_amdgcn_s_barrier()
; #define G_SCHED __builtin_amdgcn_sched_barrier(0)
; template <int GP> DI void gemm_phase(const Params& p, int l, int which, char* smem, int wv) {
;     ...
;       G_LDB(B1, 1, 1); G_STAGE(G_SB(1, 0), b3, vb0);
;       G_BAR; G_WAIT_L(0); G_MMA(0, 1, At, B1); G_BAR;
;       G_LDA(At, 1, 1); G_STAGE(G_SA(1, 0), a3, voffA);
;       G_BAR; G_WAIT_L(0); G_MMA(1, 0, At, B0); G_BAR; G_SCHED;
;       G_STAGE(G_SB(1, 1), b3, vb1);
;       G_WAIT_V(6); G_BAR; G_MMA(1, 1, At, B1); G_BAR;
	s_waitcnt lgkmcnt(0)
	s_waitcnt lgkmcnt(0)
	v_mfma_f32_16x16x32_bf16 v[30:33], v[196:199], v[164:167], v[30:33]
	v_mfma_f32_16x16x32_bf16 v[26:29], v[204:207], v[164:167], v[26:29]
	s_mov_b32 m0, s65
	s_add_u32 s100, s8, s16
	s_addc_u32 s101, s9, s17
	v_mfma_f32_16x16x32_bf16 v[22:25], v[196:199], v[172:175], v[22:25]
	v_mfma_f32_16x16x32_bf16 v[18:21], v[204:207], v[172:175], v[18:21]
	v_mfma_f32_16x16x32_bf16 v[14:17], v[196:199], v[180:183], v[14:17]
	v_mfma_f32_16x16x32_bf16 v[10:13], v[204:207], v[180:183], v[10:13]
	v_mfma_f32_16x16x32_bf16 v[6:9], v[196:199], v[188:191], v[6:9]
	v_mfma_f32_16x16x32_bf16 v[2:5], v[204:207], v[188:191], v[2:5]
	v_mfma_f32_16x16x32_bf16 v[30:33], v[200:203], v[168:171], v[30:33]
	v_mfma_f32_16x16x32_bf16 v[26:29], v[238:241], v[168:171], v[26:29]
	v_mfma_f32_16x16x32_bf16 v[22:25], v[200:203], v[176:179], v[22:25]
	v_mfma_f32_16x16x32_bf16 v[18:21], v[238:241], v[176:179], v[18:21]
	v_mfma_f32_16x16x32_bf16 v[14:17], v[200:203], v[184:187], v[14:17]
	v_mfma_f32_16x16x32_bf16 v[10:13], v[238:241], v[184:187], v[10:13]
	v_mfma_f32_16x16x32_bf16 v[6:9], v[200:203], v[192:195], v[6:9]
	v_mfma_f32_16x16x32_bf16 v[2:5], v[238:241], v[192:195], v[2:5]
	s_barrier
	ds_read_b128 v[164:167], v211 offset:49152
	ds_read_b128 v[168:171], v211 offset:50176
	ds_read_b128 v[172:175], v211 offset:51200
	ds_read_b128 v[176:179], v211 offset:52224
	ds_read_b128 v[180:183], v211 offset:53248
	ds_read_b128 v[184:187], v211 offset:54272
	ds_read_b128 v[188:191], v211 offset:55296
	ds_read_b128 v[192:195], v211 offset:56320
	global_load_lds_dwordx4 v132, s[100:101]
	s_mov_b32 m0, s66
	s_nop 0
	global_load_lds_dwordx4 v134, s[100:101]
	s_barrier
	s_waitcnt lgkmcnt(0)
	s_waitcnt lgkmcnt(0)
	v_mfma_f32_16x16x32_bf16 v[66:69], v[148:151], v[164:167], v[66:69]
	v_mfma_f32_16x16x32_bf16 v[70:73], v[156:159], v[164:167], v[70:73]
	s_mov_b32 m0, s67
	s_add_u32 s100, s6, s16
	s_addc_u32 s101, s7, s17
	v_mfma_f32_16x16x32_bf16 v[74:77], v[148:151], v[172:175], v[74:77]
	v_mfma_f32_16x16x32_bf16 v[78:81], v[156:159], v[172:175], v[78:81]
	v_mfma_f32_16x16x32_bf16 v[82:85], v[148:151], v[180:183], v[82:85]
	v_mfma_f32_16x16x32_bf16 v[86:89], v[156:159], v[180:183], v[86:89]
	v_mfma_f32_16x16x32_bf16 v[90:93], v[148:151], v[188:191], v[90:93]
	v_mfma_f32_16x16x32_bf16 v[94:97], v[156:159], v[188:191], v[94:97]
	v_mfma_f32_16x16x32_bf16 v[66:69], v[152:155], v[168:171], v[66:69]
	v_mfma_f32_16x16x32_bf16 v[70:73], v[160:163], v[168:171], v[70:73]
	v_mfma_f32_16x16x32_bf16 v[74:77], v[152:155], v[176:179], v[74:77]
	v_mfma_f32_16x16x32_bf16 v[78:81], v[160:163], v[176:179], v[78:81]
	v_mfma_f32_16x16x32_bf16 v[82:85], v[152:155], v[184:187], v[82:85]
	v_mfma_f32_16x16x32_bf16 v[86:89], v[160:163], v[184:187], v[86:89]
	v_mfma_f32_16x16x32_bf16 v[90:93], v[152:155], v[192:195], v[90:93]
	v_mfma_f32_16x16x32_bf16 v[94:97], v[160:163], v[192:195], v[94:97]
	s_barrier
	global_load_lds_dwordx4 v130, s[100:101]
	s_mov_b32 m0, s68
	s_nop 0
	global_load_lds_dwordx4 v142, s[100:101]
	s_waitcnt vmcnt(6)
	s_barrier
	v_mfma_f32_16x16x32_bf16 v[98:101], v[196:199], v[164:167], v[98:101]
	v_mfma_f32_16x16x32_bf16 v[102:105], v[204:207], v[164:167], v[102:105]
	s_add_i32 m0, s23, 0xc000
	v_mfma_f32_16x16x32_bf16 v[106:109], v[196:199], v[172:175], v[106:109]
	v_mfma_f32_16x16x32_bf16 v[110:113], v[204:207], v[172:175], v[110:113]
	v_mfma_f32_16x16x32_bf16 v[114:117], v[196:199], v[180:183], v[114:117]
	v_mfma_f32_16x16x32_bf16 v[118:121], v[204:207], v[180:183], v[118:121]
	v_mfma_f32_16x16x32_bf16 v[122:125], v[196:199], v[188:191], v[122:125]
	v_mfma_f32_16x16x32_bf16 v[126:129], v[204:207], v[188:191], v[126:129]
	v_mfma_f32_16x16x32_bf16 v[98:101], v[200:203], v[168:171], v[98:101]
	s_add_i32 s50, s50, 2
	s_add_u32 s2, s2, 0x100
	s_addc_u32 s3, s3, 0
	v_mfma_f32_16x16x32_bf16 v[102:105], v[238:241], v[168:171], v[102:105]
	s_add_u32 s8, s28, s2
	s_addc_u32 s9, s29, s3
	v_mfma_f32_16x16x32_bf16 v[106:109], v[200:203], v[176:179], v[106:109]
	s_add_u32 s100, s8, 0x80080
	s_addc_u32 s101, s9, 0
	v_mfma_f32_16x16x32_bf16 v[110:113], v[238:241], v[176:179], v[110:113]
	s_add_u32 s8, s8, 0x100
	s_addc_u32 s9, s9, 0
	v_mfma_f32_16x16x32_bf16 v[114:117], v[200:203], v[184:187], v[114:117]
	s_add_u32 s6, s74, s2
	s_addc_u32 s7, s75, s3
	v_mfma_f32_16x16x32_bf16 v[118:121], v[238:241], v[184:187], v[118:121]
	v_mfma_f32_16x16x32_bf16 v[122:125], v[200:203], v[192:195], v[122:125]
	v_mfma_f32_16x16x32_bf16 v[126:129], v[238:241], v[192:195], v[126:129]
	s_cmp_gt_u32 s50, 29
	s_barrier
	s_cbranch_scc1 .LBB0_219
	s_cmpk_lg_i32 s2, 0xf00
	s_cbranch_scc1 .Lkf_top
